# P0 rows loop: loop-invariant kernarg pointers loaded once in the preheader instead of 16 s_loads per trip
# speedup vs baseline: 1.0050x; 1.0050x over previous
; #define INP(k) ((const float*)(GAS const float*)KARG64(8 * (k)))
; #define R1 ((float*)(WSP() + WS_R1))
; __global__ void __launch_bounds__(NWAVES * 64, 2) hybrid_fwd(Params P) {
;     ...
;         for (int m0 = gw * 4; m0 < MAINR + NMETA; m0 += NGW * 4) {
;             const float* src[4]; bf16* dst[4]; float* rr[4];
; #pragma unroll
;             for (int r = 0; r < 4; ++r) { const int m = m0 + r; src[r] = m < MAINR ? INP(0) + (size_t)m * 1024 : INP(1) + (size_t)(m - MAINR) * 1024; dst[r] = XB + (size_t)m * 1024; rr[r] = R1 + m; }
;             rows_to_bf16<4>(src, dst, rr, lane);
;         }
.LBB0_60:
	s_or_b64 exec, exec, s[4:5]
	s_cmpk_gt_i32 s57, 0x2003
	s_cbranch_scc1 .LBB0_87
	s_load_dwordx2 s[70:71], s[0:1], 0x0
	s_load_dwordx2 s[74:75], s[0:1], 0x8
	s_load_dwordx2 s[72:73], s[0:1], 0xf0
	s_waitcnt lgkmcnt(0)
	v_mbcnt_lo_u32_b32 v2, -1, 0
	s_lshl_b32 s6, s57, 2
	s_lshl_b32 s12, s3, 5
	v_mbcnt_hi_u32_b32 v70, -1, v2
	s_ashr_i32 s7, s6, 31
	s_ashr_i32 s13, s12, 31
	v_and_b32_e32 v2, 64, v70
	v_mov_b32_e32 v69, 0
	s_mov_b32 s11, 0
	v_cmp_eq_u32_e64 s[4:5], 0, v174
	s_lshl_b64 s[14:15], s[6:7], 12
	s_lshl_b64 s[16:17], s[12:13], 12
	v_lshlrev_b32_e32 v1, 4, v174
	v_add_u32_e32 v71, 64, v2
	v_xor_b32_e32 v72, 1, v70
	v_xor_b32_e32 v73, 2, v70
	v_xor_b32_e32 v74, 4, v70
	v_xor_b32_e32 v75, 8, v70
	v_xor_b32_e32 v76, 16, v70
	v_xor_b32_e32 v77, 32, v70
	v_mov_b32_e32 v78, 0x358637bd
	s_mov_b64 s[18:19], 0x3200000
	s_mov_b32 s33, 0x3200000
	s_branch .LBB0_63

; #define INP(k) ((const float*)(GAS const float*)KARG64(8 * (k)))
; #define R1 ((float*)(WSP() + WS_R1))
; __global__ void __launch_bounds__(NWAVES * 64, 2) hybrid_fwd(Params P) {
;     ...
;         for (int m0 = gw * 4; m0 < MAINR + NMETA; m0 += NGW * 4) {
;             const float* src[4]; bf16* dst[4]; float* rr[4];
; #pragma unroll
;             for (int r = 0; r < 4; ++r) { const int m = m0 + r; src[r] = m < MAINR ? INP(0) + (size_t)m * 1024 : INP(1) + (size_t)(m - MAINR) * 1024; dst[r] = XB + (size_t)m * 1024; rr[r] = R1 + m; }
.LBB0_63:
	s_cmpk_gt_i32 s6, 0x7fff
	s_mov_b64 s[20:21], -1
	s_cbranch_scc0 .LBB0_65
	s_mov_b64 s[20:21], s[0:1]
	s_mov_b64 s[22:23], s[74:75]
	s_add_i32 s10, s6, 0xffff8000
	s_lshl_b64 s[24:25], s[10:11], 12
	s_mov_b32 s10, s6
	s_mov_b64 s[20:21], 0
	s_waitcnt lgkmcnt(0)
	s_add_u32 s44, s22, s24
	s_addc_u32 s45, s23, s25
	s_mov_b64 s[34:35], s[10:11]
.LBB0_65:
	s_andn2_b64 vcc, exec, s[20:21]
	s_cbranch_vccnz .LBB0_67
	s_mov_b64 s[20:21], s[0:1]
	s_mov_b64 s[20:21], s[70:71]
	s_mov_b64 s[34:35], s[6:7]
	s_waitcnt lgkmcnt(0)
	s_add_u32 s44, s20, s14
	s_addc_u32 s45, s21, s15
.LBB0_67:
	s_mov_b64 s[20:21], s[0:1]
	s_mov_b64 s[40:41], s[72:73]
	s_mov_b64 s[20:21], s[0:1]
	s_mov_b64 s[46:47], s[72:73]
	s_add_u32 s20, s6, 1
	s_addc_u32 s21, s7, 0
	s_cmp_lt_i32 s20, 0x8000
	s_mov_b64 s[22:23], -1
	s_cbranch_scc1 .LBB0_69
	s_mov_b64 s[22:23], s[0:1]
	s_mov_b64 s[24:25], s[74:75]
	s_add_i32 s10, s6, 0xffff8001
	s_lshl_b64 s[26:27], s[10:11], 12
	s_mov_b32 s10, s20
	s_mov_b64 s[22:23], 0
	s_waitcnt lgkmcnt(0)
	s_add_u32 s48, s24, s26
	s_addc_u32 s49, s25, s27
	s_mov_b64 s[28:29], s[10:11]
.LBB0_69:
	s_andn2_b64 vcc, exec, s[22:23]
	s_cbranch_vccnz .LBB0_71
	s_mov_b64 s[22:23], s[0:1]
	s_mov_b64 s[22:23], s[70:71]
	s_mov_b64 s[28:29], s[20:21]
	s_waitcnt lgkmcnt(0)
	s_add_u32 s10, s22, s14
	s_addc_u32 s22, s23, s15
	s_add_u32 s48, s10, 0x1000
	s_addc_u32 s49, s22, 0
.LBB0_71:
	s_mov_b64 s[20:21], s[0:1]
	s_mov_b64 s[30:31], s[72:73]
	s_mov_b64 s[20:21], s[0:1]
	s_mov_b64 s[42:43], s[72:73]
	s_add_u32 s22, s6, 2
	s_addc_u32 s23, s7, 0
	s_cmp_lt_i32 s22, 0x8000
	s_mov_b64 s[24:25], -1
	s_cbranch_scc1 .LBB0_73
	s_mov_b64 s[20:21], s[0:1]
	s_mov_b64 s[20:21], s[74:75]
	s_add_i32 s10, s6, 0xffff8002
	s_lshl_b64 s[26:27], s[10:11], 12
	s_mov_b32 s10, s22
	s_mov_b64 s[24:25], 0
	s_waitcnt lgkmcnt(0)
	s_add_u32 s50, s20, s26
	s_addc_u32 s51, s21, s27
	s_mov_b64 s[20:21], s[10:11]
.LBB0_73:
	s_andn2_b64 vcc, exec, s[24:25]
	s_cbranch_vccnz .LBB0_75
	s_mov_b64 s[20:21], s[0:1]
	s_mov_b64 s[20:21], s[70:71]
	s_waitcnt lgkmcnt(0)
	s_add_u32 s10, s20, s14
	s_addc_u32 s20, s21, s15
	s_add_u32 s50, s10, 0x2000
	s_addc_u32 s51, s20, 0
	s_mov_b64 s[20:21], s[22:23]
.LBB0_75:
	s_mov_b64 s[22:23], s[0:1]
	s_mov_b64 s[24:25], s[72:73]
	s_mov_b64 s[22:23], s[0:1]
	s_mov_b64 s[36:37], s[72:73]
	s_add_u32 s26, s6, 3
	s_addc_u32 s27, s7, 0
	s_cmp_lt_i32 s26, 0x8000
	s_mov_b64 s[52:53], -1
	s_cbranch_scc1 .LBB0_77
	s_mov_b64 s[22:23], s[0:1]
	s_mov_b64 s[22:23], s[74:75]
	s_add_i32 s10, s6, 0xffff8003
	s_lshl_b64 s[38:39], s[10:11], 12
	s_mov_b32 s10, s26
	s_mov_b64 s[52:53], 0
	s_waitcnt lgkmcnt(0)
	s_add_u32 s54, s22, s38
	s_addc_u32 s55, s23, s39
	s_mov_b64 s[22:23], s[10:11]
.LBB0_77:
	s_andn2_b64 vcc, exec, s[52:53]
	s_cbranch_vccnz .LBB0_79
	s_mov_b64 s[22:23], s[0:1]
	s_mov_b64 s[22:23], s[70:71]
	s_waitcnt lgkmcnt(0)
	s_add_u32 s10, s22, s14
	s_addc_u32 s22, s23, s15
	s_add_u32 s54, s10, 0x3000
	s_addc_u32 s55, s22, 0
	s_mov_b64 s[22:23], s[26:27]
.LBB0_79:
	s_mov_b64 s[26:27], s[0:1]
	s_mov_b64 s[52:53], s[0:1]
	s_mov_b64 s[26:27], s[72:73]
	s_cmp_eq_u32 s59, 0
	s_cbranch_scc1 .Lrows_ld
	s_mov_b32 s59, 0
	s_waitcnt vmcnt(0) lgkmcnt(0)
	v_mov_b64_e32 v[2:3], v[100:101]
	v_mov_b64_e32 v[4:5], v[102:103]
	v_mov_b64_e32 v[6:7], v[104:105]
	v_mov_b64_e32 v[8:9], v[106:107]
	v_mov_b64_e32 v[10:11], v[108:109]
	v_mov_b64_e32 v[12:13], v[110:111]
	v_mov_b64_e32 v[14:15], v[112:113]
	v_mov_b64_e32 v[16:17], v[114:115]
	v_mov_b64_e32 v[18:19], v[116:117]
	v_mov_b64_e32 v[20:21], v[118:119]
	v_mov_b64_e32 v[22:23], v[120:121]
	v_mov_b64_e32 v[24:25], v[122:123]
	v_mov_b64_e32 v[26:27], v[124:125]
	v_mov_b64_e32 v[28:29], v[126:127]
	v_mov_b64_e32 v[30:31], v[128:129]
	v_mov_b64_e32 v[32:33], v[130:131]
	v_mov_b64_e32 v[34:35], v[132:133]
	v_mov_b64_e32 v[36:37], v[134:135]
	v_mov_b64_e32 v[38:39], v[136:137]
	v_mov_b64_e32 v[40:41], v[138:139]
	v_mov_b64_e32 v[42:43], v[140:141]
	v_mov_b64_e32 v[44:45], v[142:143]
	v_mov_b64_e32 v[46:47], v[144:145]
	v_mov_b64_e32 v[48:49], v[146:147]
	v_mov_b64_e32 v[50:51], v[148:149]
	v_mov_b64_e32 v[52:53], v[150:151]
	v_mov_b64_e32 v[54:55], v[152:153]
	v_mov_b64_e32 v[56:57], v[154:155]
	v_mov_b64_e32 v[58:59], v[156:157]
	v_mov_b64_e32 v[60:61], v[158:159]
	v_mov_b64_e32 v[62:63], v[160:161]
	v_mov_b64_e32 v[64:65], v[162:163]
	s_branch .Lrows_go

; __device__ __forceinline__ float sq4(f32x4 v) { return (v[0] * v[0] + v[1] * v[1]) + (v[2] * v[2] + v[3] * v[3]); }
; __device__ __forceinline__ float wave_sum(float v) {
; #pragma unroll
;     for (int o = 1; o < 64; o <<= 1) v += __shfl_xor(v, o);
;     return v;
; }
; template <int NR> __device__ __forceinline__ void rows_to_bf16(const float* const* src, bf16* const* dst, float* const* r1, int lane) {
;     ...
; #pragma unroll
;     for (int r = 0; r < NR; ++r) {
;         float s = 0.f;
; #pragma unroll
;         for (int j = 0; j < 4; ++j) s += sq4(v[r][j]);
;         s = wave_sum(s);
;         if (lane == 0) *r1[r] = __builtin_amdgcn_rsqf(s * (1.f / 1024.f) + EPS);
;         u32x2* o8 = (u32x2*)dst[r] + lane;
.Lrows_go:
	v_cmp_lt_i32_e32 vcc, v72, v71
	s_mov_b64 s[44:45], s[72:73]
	s_waitcnt vmcnt(15)
	v_mul_f32_e32 v80, v65, v65
	v_cndmask_b32_e32 v68, v70, v72, vcc
	v_lshlrev_b32_e32 v79, 2, v68
	v_mul_f32_e32 v68, v63, v63
	s_waitcnt vmcnt(14)
	v_mul_f32_e32 v81, v59, v59
	v_mul_f32_e32 v82, v61, v61
	s_waitcnt vmcnt(13)
	v_mul_f32_e32 v83, v55, v55
	v_mul_f32_e32 v84, v57, v57
	v_fmac_f32_e32 v68, v62, v62
	v_fmac_f32_e32 v80, v64, v64
	v_fmac_f32_e32 v81, v58, v58
	v_fmac_f32_e32 v82, v60, v60
	s_waitcnt vmcnt(12)
	v_mul_f32_e32 v85, v51, v51
	v_mul_f32_e32 v86, v53, v53
	v_fmac_f32_e32 v83, v54, v54
	v_fmac_f32_e32 v84, v56, v56
	v_add_f32_e32 v68, v68, v80
	v_add_f32_e32 v80, v81, v82
	v_fmac_f32_e32 v85, v50, v50
	v_fmac_f32_e32 v86, v52, v52
	v_add_f32_e32 v81, v83, v84
	v_add_f32_e32 v68, v68, v80
	v_add_f32_e32 v68, v68, v81
	v_add_f32_e32 v80, v85, v86
	v_add_f32_e32 v68, v68, v80
	ds_bpermute_b32 v80, v79, v68
	v_cmp_lt_i32_e32 vcc, v73, v71
	s_waitcnt lgkmcnt(0)
	v_add_f32_e32 v68, v68, v80
	v_cndmask_b32_e32 v81, v70, v73, vcc
	v_lshlrev_b32_e32 v84, 2, v81
	ds_bpermute_b32 v80, v84, v68
	v_cmp_lt_i32_e32 vcc, v74, v71
	s_waitcnt lgkmcnt(0)
	v_add_f32_e32 v68, v68, v80
	v_cndmask_b32_e32 v81, v70, v74, vcc
	v_lshlrev_b32_e32 v82, 2, v81
	ds_bpermute_b32 v80, v82, v68
	v_cmp_lt_i32_e32 vcc, v75, v71
	s_waitcnt lgkmcnt(0)
	v_add_f32_e32 v68, v68, v80
	v_cndmask_b32_e32 v81, v70, v75, vcc
	v_lshlrev_b32_e32 v83, 2, v81
	ds_bpermute_b32 v81, v83, v68
	v_cmp_lt_i32_e32 vcc, v76, v71
	s_waitcnt lgkmcnt(0)
	v_add_f32_e32 v68, v68, v81
	v_cndmask_b32_e32 v80, v70, v76, vcc
	v_lshlrev_b32_e32 v80, 2, v80
	ds_bpermute_b32 v85, v80, v68
	v_cmp_lt_i32_e32 vcc, v77, v71
	s_waitcnt lgkmcnt(0)
	v_add_f32_e32 v68, v68, v85
	v_cndmask_b32_e32 v81, v70, v77, vcc
	v_lshlrev_b32_e32 v81, 2, v81
	ds_bpermute_b32 v85, v81, v68
	s_and_saveexec_b64 s[38:39], s[4:5]
	s_xor_b64 s[48:49], exec, s[38:39]
	s_cbranch_execz .LBB0_81
	s_waitcnt lgkmcnt(0)
	v_add_f32_e32 v68, v68, v85
	v_fmamk_f32 v68, v68, 0x3a800000, v78
	v_rsq_f32_e32 v68, v68
	s_lshl_b64 s[38:39], s[34:35], 2
	s_add_u32 s38, s46, s38
	s_addc_u32 s39, s47, s39
	global_store_dword v69, v68, s[38:39]
